# v088 + 64-byte alignment of the six GEMM K-loop heads
# baseline (speedup 1.0000x reference)
.LBB0_350:
	s_ashr_i32 s15, s14, 31
	s_lshl_b64 s[16:17], s[14:15], 20
	s_add_u32 s16, s20, s16
	s_addc_u32 s17, s41, s17
	s_and_b64 s[24:25], s[0:1], exec
	s_cselect_b32 s15, s17, s31
	s_cselect_b32 s62, s16, s30
	s_ashr_i32 s13, s12, 31
	s_lshl_b64 s[24:25], s[12:13], 20
	s_add_u32 s24, s42, s24
	s_addc_u32 s25, s43, s25
	s_and_b64 s[38:39], s[0:1], exec
	s_cselect_b32 s13, s25, s29
	s_cselect_b32 s63, s24, s28
	s_add_u32 s68, s28, 0x100
	s_addc_u32 s69, s29, 0
	s_add_u32 s28, s30, 0x80080
	v_mov_b32_e32 v2, 0
	s_addc_u32 s29, s31, 0
	s_mov_b32 s70, -2
	v_mov_b32_e32 v3, v2
	v_mov_b32_e32 v4, v2
	v_mov_b32_e32 v5, v2
	v_mov_b32_e32 v6, v2
	v_mov_b32_e32 v7, v2
	v_mov_b32_e32 v8, v2
	v_mov_b32_e32 v9, v2
	v_mov_b32_e32 v18, v2
	v_mov_b32_e32 v19, v2
	v_mov_b32_e32 v20, v2
	v_mov_b32_e32 v21, v2
	v_mov_b32_e32 v22, v2
	v_mov_b32_e32 v23, v2
	v_mov_b32_e32 v24, v2
	v_mov_b32_e32 v25, v2
	v_mov_b32_e32 v34, v2
	v_mov_b32_e32 v35, v2
	v_mov_b32_e32 v36, v2
	v_mov_b32_e32 v37, v2
	v_mov_b32_e32 v38, v2
	v_mov_b32_e32 v39, v2
	v_mov_b32_e32 v40, v2
	v_mov_b32_e32 v41, v2
	v_mov_b32_e32 v50, v2
	v_mov_b32_e32 v51, v2
	v_mov_b32_e32 v52, v2
	v_mov_b32_e32 v53, v2
	v_mov_b32_e32 v54, v2
	v_mov_b32_e32 v55, v2
	v_mov_b32_e32 v56, v2
	v_mov_b32_e32 v57, v2
	v_mov_b32_e32 v10, v2
	v_mov_b32_e32 v11, v2
	v_mov_b32_e32 v12, v2
	v_mov_b32_e32 v13, v2
	v_mov_b32_e32 v14, v2
	v_mov_b32_e32 v15, v2
	v_mov_b32_e32 v16, v2
	v_mov_b32_e32 v17, v2
	v_mov_b32_e32 v26, v2
	v_mov_b32_e32 v27, v2
	v_mov_b32_e32 v28, v2
	v_mov_b32_e32 v29, v2
	v_mov_b32_e32 v30, v2
	v_mov_b32_e32 v31, v2
	v_mov_b32_e32 v32, v2
	v_mov_b32_e32 v33, v2
	v_mov_b32_e32 v42, v2
	v_mov_b32_e32 v43, v2
	v_mov_b32_e32 v44, v2
	v_mov_b32_e32 v45, v2
	v_mov_b32_e32 v46, v2
	v_mov_b32_e32 v47, v2
	v_mov_b32_e32 v48, v2
	v_mov_b32_e32 v49, v2
	v_mov_b32_e32 v58, v2
	v_mov_b32_e32 v59, v2
	v_mov_b32_e32 v60, v2
	v_mov_b32_e32 v61, v2
	v_mov_b32_e32 v62, v2
	v_mov_b32_e32 v63, v2
	v_mov_b32_e32 v64, v2
	v_mov_b32_e32 v65, v2
	v_mov_b32_e32 v66, v2
	v_mov_b32_e32 v67, v2
	v_mov_b32_e32 v68, v2
	v_mov_b32_e32 v69, v2
	v_mov_b32_e32 v70, v2
	v_mov_b32_e32 v71, v2
	v_mov_b32_e32 v72, v2
	v_mov_b32_e32 v73, v2
	v_mov_b32_e32 v82, v2
	v_mov_b32_e32 v83, v2
	v_mov_b32_e32 v84, v2
	v_mov_b32_e32 v85, v2
	v_mov_b32_e32 v86, v2
	v_mov_b32_e32 v87, v2
	v_mov_b32_e32 v88, v2
	v_mov_b32_e32 v89, v2
	v_mov_b32_e32 v98, v2
	v_mov_b32_e32 v99, v2
	v_mov_b32_e32 v100, v2
	v_mov_b32_e32 v101, v2
	v_mov_b32_e32 v102, v2
	v_mov_b32_e32 v103, v2
	v_mov_b32_e32 v104, v2
	v_mov_b32_e32 v105, v2
	v_mov_b32_e32 v114, v2
	v_mov_b32_e32 v115, v2
	v_mov_b32_e32 v116, v2
	v_mov_b32_e32 v117, v2
	v_mov_b32_e32 v118, v2
	v_mov_b32_e32 v119, v2
	v_mov_b32_e32 v120, v2
	v_mov_b32_e32 v121, v2
	v_mov_b32_e32 v74, v2
	v_mov_b32_e32 v75, v2
	v_mov_b32_e32 v76, v2
	v_mov_b32_e32 v77, v2
	v_mov_b32_e32 v78, v2
	v_mov_b32_e32 v79, v2
	v_mov_b32_e32 v80, v2
	v_mov_b32_e32 v81, v2
	v_mov_b32_e32 v90, v2
	v_mov_b32_e32 v91, v2
	v_mov_b32_e32 v92, v2
	v_mov_b32_e32 v93, v2
	v_mov_b32_e32 v94, v2
	v_mov_b32_e32 v95, v2
	v_mov_b32_e32 v96, v2
	v_mov_b32_e32 v97, v2
	v_mov_b32_e32 v106, v2
	v_mov_b32_e32 v107, v2
	v_mov_b32_e32 v108, v2
	v_mov_b32_e32 v109, v2
	v_mov_b32_e32 v110, v2
	v_mov_b32_e32 v111, v2
	v_mov_b32_e32 v112, v2
	v_mov_b32_e32 v113, v2
	v_mov_b32_e32 v122, v2
	v_mov_b32_e32 v123, v2
	v_mov_b32_e32 v124, v2
	v_mov_b32_e32 v125, v2
	v_mov_b32_e32 v126, v2
	v_mov_b32_e32 v127, v2
	v_mov_b32_e32 v128, v2
	v_mov_b32_e32 v129, v2
	v_add_u32_e32 v212, 0x10000, v151
	.p2align 6

.LBB0_662:
	s_ashr_i32 s11, s10, 31
	s_lshl_b64 s[12:13], s[10:11], 20
	s_add_u32 s12, s20, s12
	s_addc_u32 s13, s30, s13
	s_and_b64 s[14:15], s[0:1], exec
	s_cselect_b32 s11, s13, s25
	s_cselect_b32 s49, s12, s24
	s_ashr_i32 s9, s8, 31
	s_lshl_b64 s[14:15], s[8:9], 20
	s_add_u32 s14, s31, s14
	s_addc_u32 s15, s36, s15
	s_and_b64 s[28:29], s[0:1], exec
	s_cselect_b32 s9, s15, s17
	s_cselect_b32 s54, s14, s16
	s_add_u32 s55, s16, 0x100
	s_addc_u32 s56, s17, 0
	s_add_u32 s16, s24, 0x80080
	v_mov_b32_e32 v2, 0
	s_addc_u32 s17, s25, 0
	s_mov_b32 s57, -2
	v_mov_b32_e32 v3, v2
	v_mov_b32_e32 v4, v2
	v_mov_b32_e32 v5, v2
	v_mov_b32_e32 v6, v2
	v_mov_b32_e32 v7, v2
	v_mov_b32_e32 v8, v2
	v_mov_b32_e32 v9, v2
	v_mov_b32_e32 v10, v2
	v_mov_b32_e32 v11, v2
	v_mov_b32_e32 v12, v2
	v_mov_b32_e32 v13, v2
	v_mov_b32_e32 v18, v2
	v_mov_b32_e32 v19, v2
	v_mov_b32_e32 v20, v2
	v_mov_b32_e32 v21, v2
	v_mov_b32_e32 v26, v2
	v_mov_b32_e32 v27, v2
	v_mov_b32_e32 v28, v2
	v_mov_b32_e32 v29, v2
	v_mov_b32_e32 v34, v2
	v_mov_b32_e32 v35, v2
	v_mov_b32_e32 v36, v2
	v_mov_b32_e32 v37, v2
	v_mov_b32_e32 v42, v2
	v_mov_b32_e32 v43, v2
	v_mov_b32_e32 v44, v2
	v_mov_b32_e32 v45, v2
	v_mov_b32_e32 v50, v2
	v_mov_b32_e32 v51, v2
	v_mov_b32_e32 v52, v2
	v_mov_b32_e32 v53, v2
	v_mov_b32_e32 v14, v2
	v_mov_b32_e32 v15, v2
	v_mov_b32_e32 v16, v2
	v_mov_b32_e32 v17, v2
	v_mov_b32_e32 v22, v2
	v_mov_b32_e32 v23, v2
	v_mov_b32_e32 v24, v2
	v_mov_b32_e32 v25, v2
	v_mov_b32_e32 v30, v2
	v_mov_b32_e32 v31, v2
	v_mov_b32_e32 v32, v2
	v_mov_b32_e32 v33, v2
	v_mov_b32_e32 v38, v2
	v_mov_b32_e32 v39, v2
	v_mov_b32_e32 v40, v2
	v_mov_b32_e32 v41, v2
	v_mov_b32_e32 v46, v2
	v_mov_b32_e32 v47, v2
	v_mov_b32_e32 v48, v2
	v_mov_b32_e32 v49, v2
	v_mov_b32_e32 v54, v2
	v_mov_b32_e32 v55, v2
	v_mov_b32_e32 v56, v2
	v_mov_b32_e32 v57, v2
	v_mov_b32_e32 v58, v2
	v_mov_b32_e32 v59, v2
	v_mov_b32_e32 v60, v2
	v_mov_b32_e32 v61, v2
	v_mov_b32_e32 v62, v2
	v_mov_b32_e32 v63, v2
	v_mov_b32_e32 v64, v2
	v_mov_b32_e32 v65, v2
	v_mov_b32_e32 v66, v2
	v_mov_b32_e32 v67, v2
	v_mov_b32_e32 v68, v2
	v_mov_b32_e32 v69, v2
	v_mov_b32_e32 v70, v2
	v_mov_b32_e32 v71, v2
	v_mov_b32_e32 v72, v2
	v_mov_b32_e32 v73, v2
	v_mov_b32_e32 v74, v2
	v_mov_b32_e32 v75, v2
	v_mov_b32_e32 v76, v2
	v_mov_b32_e32 v77, v2
	v_mov_b32_e32 v82, v2
	v_mov_b32_e32 v83, v2
	v_mov_b32_e32 v84, v2
	v_mov_b32_e32 v85, v2
	v_mov_b32_e32 v90, v2
	v_mov_b32_e32 v91, v2
	v_mov_b32_e32 v92, v2
	v_mov_b32_e32 v93, v2
	v_mov_b32_e32 v98, v2
	v_mov_b32_e32 v99, v2
	v_mov_b32_e32 v100, v2
	v_mov_b32_e32 v101, v2
	v_mov_b32_e32 v106, v2
	v_mov_b32_e32 v107, v2
	v_mov_b32_e32 v108, v2
	v_mov_b32_e32 v109, v2
	v_mov_b32_e32 v114, v2
	v_mov_b32_e32 v115, v2
	v_mov_b32_e32 v116, v2
	v_mov_b32_e32 v117, v2
	v_mov_b32_e32 v78, v2
	v_mov_b32_e32 v79, v2
	v_mov_b32_e32 v80, v2
	v_mov_b32_e32 v81, v2
	v_mov_b32_e32 v86, v2
	v_mov_b32_e32 v87, v2
	v_mov_b32_e32 v88, v2
	v_mov_b32_e32 v89, v2
	v_mov_b32_e32 v94, v2
	v_mov_b32_e32 v95, v2
	v_mov_b32_e32 v96, v2
	v_mov_b32_e32 v97, v2
	v_mov_b32_e32 v102, v2
	v_mov_b32_e32 v103, v2
	v_mov_b32_e32 v104, v2
	v_mov_b32_e32 v105, v2
	v_mov_b32_e32 v110, v2
	v_mov_b32_e32 v111, v2
	v_mov_b32_e32 v112, v2
	v_mov_b32_e32 v113, v2
	v_mov_b32_e32 v118, v2
	v_mov_b32_e32 v119, v2
	v_mov_b32_e32 v120, v2
	v_mov_b32_e32 v121, v2
	v_mov_b32_e32 v122, v2
	v_mov_b32_e32 v123, v2
	v_mov_b32_e32 v124, v2
	v_mov_b32_e32 v125, v2
	v_mov_b32_e32 v126, v2
	v_mov_b32_e32 v127, v2
	v_mov_b32_e32 v128, v2
	v_mov_b32_e32 v129, v2
	v_add_u32_e32 v212, 0x10000, v147
	.p2align 6

.LBB0_1028:
	s_ashr_i32 s13, s12, 31
	s_lshl_b64 s[14:15], s[12:13], 20
	s_add_u32 s14, s42, s14
	s_addc_u32 s15, s43, s15
	s_and_b64 s[16:17], s[36:37], exec
	s_cselect_b32 s13, s15, s29
	s_cselect_b32 s59, s14, s28
	s_ashr_i32 s11, s10, 31
	s_lshl_b64 s[16:17], s[10:11], 20
	s_add_u32 s16, s38, s16
	s_addc_u32 s17, s39, s17
	s_and_b64 s[30:31], s[36:37], exec
	s_cselect_b32 s11, s17, s25
	s_cselect_b32 s60, s16, s24
	s_add_u32 s61, s24, 0x100
	s_addc_u32 s62, s25, 0
	s_add_u32 s24, s28, 0x80080
	v_mov_b32_e32 v2, 0
	s_addc_u32 s25, s29, 0
	s_mov_b32 s63, -2
	v_mov_b32_e32 v3, v2
	v_mov_b32_e32 v4, v2
	v_mov_b32_e32 v5, v2
	v_mov_b32_e32 v6, v2
	v_mov_b32_e32 v7, v2
	v_mov_b32_e32 v8, v2
	v_mov_b32_e32 v9, v2
	v_mov_b32_e32 v18, v2
	v_mov_b32_e32 v19, v2
	v_mov_b32_e32 v20, v2
	v_mov_b32_e32 v21, v2
	v_mov_b32_e32 v22, v2
	v_mov_b32_e32 v23, v2
	v_mov_b32_e32 v24, v2
	v_mov_b32_e32 v25, v2
	v_mov_b32_e32 v34, v2
	v_mov_b32_e32 v35, v2
	v_mov_b32_e32 v36, v2
	v_mov_b32_e32 v37, v2
	v_mov_b32_e32 v38, v2
	v_mov_b32_e32 v39, v2
	v_mov_b32_e32 v40, v2
	v_mov_b32_e32 v41, v2
	v_mov_b32_e32 v50, v2
	v_mov_b32_e32 v51, v2
	v_mov_b32_e32 v52, v2
	v_mov_b32_e32 v53, v2
	v_mov_b32_e32 v54, v2
	v_mov_b32_e32 v55, v2
	v_mov_b32_e32 v56, v2
	v_mov_b32_e32 v57, v2
	v_mov_b32_e32 v10, v2
	v_mov_b32_e32 v11, v2
	v_mov_b32_e32 v12, v2
	v_mov_b32_e32 v13, v2
	v_mov_b32_e32 v14, v2
	v_mov_b32_e32 v15, v2
	v_mov_b32_e32 v16, v2
	v_mov_b32_e32 v17, v2
	v_mov_b32_e32 v26, v2
	v_mov_b32_e32 v27, v2
	v_mov_b32_e32 v28, v2
	v_mov_b32_e32 v29, v2
	v_mov_b32_e32 v30, v2
	v_mov_b32_e32 v31, v2
	v_mov_b32_e32 v32, v2
	v_mov_b32_e32 v33, v2
	v_mov_b32_e32 v42, v2
	v_mov_b32_e32 v43, v2
	v_mov_b32_e32 v44, v2
	v_mov_b32_e32 v45, v2
	v_mov_b32_e32 v46, v2
	v_mov_b32_e32 v47, v2
	v_mov_b32_e32 v48, v2
	v_mov_b32_e32 v49, v2
	v_mov_b32_e32 v58, v2
	v_mov_b32_e32 v59, v2
	v_mov_b32_e32 v60, v2
	v_mov_b32_e32 v61, v2
	v_mov_b32_e32 v62, v2
	v_mov_b32_e32 v63, v2
	v_mov_b32_e32 v64, v2
	v_mov_b32_e32 v65, v2
	v_mov_b32_e32 v66, v2
	v_mov_b32_e32 v67, v2
	v_mov_b32_e32 v68, v2
	v_mov_b32_e32 v69, v2
	v_mov_b32_e32 v70, v2
	v_mov_b32_e32 v71, v2
	v_mov_b32_e32 v72, v2
	v_mov_b32_e32 v73, v2
	v_mov_b32_e32 v82, v2
	v_mov_b32_e32 v83, v2
	v_mov_b32_e32 v84, v2
	v_mov_b32_e32 v85, v2
	v_mov_b32_e32 v86, v2
	v_mov_b32_e32 v87, v2
	v_mov_b32_e32 v88, v2
	v_mov_b32_e32 v89, v2
	v_mov_b32_e32 v98, v2
	v_mov_b32_e32 v99, v2
	v_mov_b32_e32 v100, v2
	v_mov_b32_e32 v101, v2
	v_mov_b32_e32 v102, v2
	v_mov_b32_e32 v103, v2
	v_mov_b32_e32 v104, v2
	v_mov_b32_e32 v105, v2
	v_mov_b32_e32 v122, v2
	v_mov_b32_e32 v123, v2
	v_mov_b32_e32 v124, v2
	v_mov_b32_e32 v125, v2
	v_mov_b32_e32 v126, v2
	v_mov_b32_e32 v127, v2
	v_mov_b32_e32 v128, v2
	v_mov_b32_e32 v129, v2
	v_mov_b32_e32 v74, v2
	v_mov_b32_e32 v75, v2
	v_mov_b32_e32 v76, v2
	v_mov_b32_e32 v77, v2
	v_mov_b32_e32 v78, v2
	v_mov_b32_e32 v79, v2
	v_mov_b32_e32 v80, v2
	v_mov_b32_e32 v81, v2
	v_mov_b32_e32 v90, v2
	v_mov_b32_e32 v91, v2
	v_mov_b32_e32 v92, v2
	v_mov_b32_e32 v93, v2
	v_mov_b32_e32 v94, v2
	v_mov_b32_e32 v95, v2
	v_mov_b32_e32 v96, v2
	v_mov_b32_e32 v97, v2
	v_mov_b32_e32 v132, v2
	v_mov_b32_e32 v133, v2
	v_mov_b32_e32 v134, v2
	v_mov_b32_e32 v135, v2
	v_mov_b32_e32 v136, v2
	v_mov_b32_e32 v137, v2
	v_mov_b32_e32 v138, v2
	v_mov_b32_e32 v139, v2
	v_mov_b32_e32 v140, v2
	v_mov_b32_e32 v141, v2
	v_mov_b32_e32 v142, v2
	v_mov_b32_e32 v143, v2
	v_mov_b32_e32 v144, v2
	v_mov_b32_e32 v145, v2
	v_mov_b32_e32 v146, v2
	v_mov_b32_e32 v147, v2
	v_add_u32_e32 v212, 0x10000, v195
	.p2align 6

.LBB0_1048:
	s_ashr_i32 s11, s10, 31
	s_lshl_b64 s[12:13], s[10:11], 9
	s_add_u32 s12, s36, s12
	s_addc_u32 s13, s37, s13
	s_and_b64 s[14:15], s[0:1], exec
	s_cselect_b32 s11, s13, s25
	s_cselect_b32 s57, s12, s24
	s_ashr_i32 s9, s8, 31
	s_lshl_b64 s[14:15], s[8:9], 20
	s_add_u32 s14, s38, s14
	s_addc_u32 s15, s39, s15
	s_and_b64 s[28:29], s[0:1], exec
	s_cselect_b32 s9, s15, s17
	s_cselect_b32 s58, s14, s16
	s_add_u32 s59, s16, 0x100
	s_addc_u32 s60, s17, 0
	s_add_u32 s16, s24, 0x300100
	v_mov_b32_e32 v2, 0
	s_addc_u32 s17, s25, 0
	s_mov_b32 s61, -2
	v_mov_b32_e32 v3, v2
	v_mov_b32_e32 v4, v2
	v_mov_b32_e32 v5, v2
	v_mov_b32_e32 v6, v2
	v_mov_b32_e32 v7, v2
	v_mov_b32_e32 v8, v2
	v_mov_b32_e32 v9, v2
	v_mov_b32_e32 v18, v2
	v_mov_b32_e32 v19, v2
	v_mov_b32_e32 v20, v2
	v_mov_b32_e32 v21, v2
	v_mov_b32_e32 v22, v2
	v_mov_b32_e32 v23, v2
	v_mov_b32_e32 v24, v2
	v_mov_b32_e32 v25, v2
	v_mov_b32_e32 v34, v2
	v_mov_b32_e32 v35, v2
	v_mov_b32_e32 v36, v2
	v_mov_b32_e32 v37, v2
	v_mov_b32_e32 v38, v2
	v_mov_b32_e32 v39, v2
	v_mov_b32_e32 v40, v2
	v_mov_b32_e32 v41, v2
	v_mov_b32_e32 v50, v2
	v_mov_b32_e32 v51, v2
	v_mov_b32_e32 v52, v2
	v_mov_b32_e32 v53, v2
	v_mov_b32_e32 v54, v2
	v_mov_b32_e32 v55, v2
	v_mov_b32_e32 v56, v2
	v_mov_b32_e32 v57, v2
	v_mov_b32_e32 v10, v2
	v_mov_b32_e32 v11, v2
	v_mov_b32_e32 v12, v2
	v_mov_b32_e32 v13, v2
	v_mov_b32_e32 v14, v2
	v_mov_b32_e32 v15, v2
	v_mov_b32_e32 v16, v2
	v_mov_b32_e32 v17, v2
	v_mov_b32_e32 v26, v2
	v_mov_b32_e32 v27, v2
	v_mov_b32_e32 v28, v2
	v_mov_b32_e32 v29, v2
	v_mov_b32_e32 v30, v2
	v_mov_b32_e32 v31, v2
	v_mov_b32_e32 v32, v2
	v_mov_b32_e32 v33, v2
	v_mov_b32_e32 v42, v2
	v_mov_b32_e32 v43, v2
	v_mov_b32_e32 v44, v2
	v_mov_b32_e32 v45, v2
	v_mov_b32_e32 v46, v2
	v_mov_b32_e32 v47, v2
	v_mov_b32_e32 v48, v2
	v_mov_b32_e32 v49, v2
	v_mov_b32_e32 v58, v2
	v_mov_b32_e32 v59, v2
	v_mov_b32_e32 v60, v2
	v_mov_b32_e32 v61, v2
	v_mov_b32_e32 v62, v2
	v_mov_b32_e32 v63, v2
	v_mov_b32_e32 v64, v2
	v_mov_b32_e32 v65, v2
	v_mov_b32_e32 v66, v2
	v_mov_b32_e32 v67, v2
	v_mov_b32_e32 v68, v2
	v_mov_b32_e32 v69, v2
	v_mov_b32_e32 v70, v2
	v_mov_b32_e32 v71, v2
	v_mov_b32_e32 v72, v2
	v_mov_b32_e32 v73, v2
	v_mov_b32_e32 v82, v2
	v_mov_b32_e32 v83, v2
	v_mov_b32_e32 v84, v2
	v_mov_b32_e32 v85, v2
	v_mov_b32_e32 v86, v2
	v_mov_b32_e32 v87, v2
	v_mov_b32_e32 v88, v2
	v_mov_b32_e32 v89, v2
	v_mov_b32_e32 v98, v2
	v_mov_b32_e32 v99, v2
	v_mov_b32_e32 v100, v2
	v_mov_b32_e32 v101, v2
	v_mov_b32_e32 v102, v2
	v_mov_b32_e32 v103, v2
	v_mov_b32_e32 v104, v2
	v_mov_b32_e32 v105, v2
	v_mov_b32_e32 v122, v2
	v_mov_b32_e32 v123, v2
	v_mov_b32_e32 v124, v2
	v_mov_b32_e32 v125, v2
	v_mov_b32_e32 v126, v2
	v_mov_b32_e32 v127, v2
	v_mov_b32_e32 v128, v2
	v_mov_b32_e32 v129, v2
	v_mov_b32_e32 v74, v2
	v_mov_b32_e32 v75, v2
	v_mov_b32_e32 v76, v2
	v_mov_b32_e32 v77, v2
	v_mov_b32_e32 v78, v2
	v_mov_b32_e32 v79, v2
	v_mov_b32_e32 v80, v2
	v_mov_b32_e32 v81, v2
	v_mov_b32_e32 v90, v2
	v_mov_b32_e32 v91, v2
	v_mov_b32_e32 v92, v2
	v_mov_b32_e32 v93, v2
	v_mov_b32_e32 v94, v2
	v_mov_b32_e32 v95, v2
	v_mov_b32_e32 v96, v2
	v_mov_b32_e32 v97, v2
	v_mov_b32_e32 v132, v2
	v_mov_b32_e32 v133, v2
	v_mov_b32_e32 v134, v2
	v_mov_b32_e32 v135, v2
	v_mov_b32_e32 v136, v2
	v_mov_b32_e32 v137, v2
	v_mov_b32_e32 v138, v2
	v_mov_b32_e32 v139, v2
	v_mov_b32_e32 v140, v2
	v_mov_b32_e32 v141, v2
	v_mov_b32_e32 v142, v2
	v_mov_b32_e32 v143, v2
	v_mov_b32_e32 v144, v2
	v_mov_b32_e32 v145, v2
	v_mov_b32_e32 v146, v2
	v_mov_b32_e32 v147, v2
	v_add_u32_e32 v238, 0x10000, v210
	.p2align 6

.LBB0_1187:
	s_ashr_i32 s9, s8, 31
	s_lshl_b64 s[10:11], s[8:9], 20
	s_add_u32 s10, s28, s10
	s_addc_u32 s11, s29, s11
	s_and_b64 s[12:13], s[0:1], exec
	s_cselect_b32 s9, s11, s17
	s_cselect_b32 s55, s10, s16
	s_ashr_i32 s7, s6, 31
	s_lshl_b64 s[12:13], s[6:7], 20
	s_add_u32 s12, s30, s12
	s_addc_u32 s13, s31, s13
	s_and_b64 s[24:25], s[0:1], exec
	s_cselect_b32 s7, s13, s15
	s_cselect_b32 s56, s12, s14
	s_add_u32 s57, s14, 0x100
	s_addc_u32 s58, s15, 0
	s_add_u32 s14, s16, 0x80080
	v_mov_b32_e32 v2, 0
	s_addc_u32 s15, s17, 0
	s_mov_b32 s59, -2
	v_mov_b32_e32 v3, v2
	v_mov_b32_e32 v4, v2
	v_mov_b32_e32 v5, v2
	v_mov_b32_e32 v10, v2
	v_mov_b32_e32 v11, v2
	v_mov_b32_e32 v12, v2
	v_mov_b32_e32 v13, v2
	v_mov_b32_e32 v18, v2
	v_mov_b32_e32 v19, v2
	v_mov_b32_e32 v20, v2
	v_mov_b32_e32 v21, v2
	v_mov_b32_e32 v26, v2
	v_mov_b32_e32 v27, v2
	v_mov_b32_e32 v28, v2
	v_mov_b32_e32 v29, v2
	v_mov_b32_e32 v34, v2
	v_mov_b32_e32 v35, v2
	v_mov_b32_e32 v36, v2
	v_mov_b32_e32 v37, v2
	v_mov_b32_e32 v42, v2
	v_mov_b32_e32 v43, v2
	v_mov_b32_e32 v44, v2
	v_mov_b32_e32 v45, v2
	v_mov_b32_e32 v50, v2
	v_mov_b32_e32 v51, v2
	v_mov_b32_e32 v52, v2
	v_mov_b32_e32 v53, v2
	v_mov_b32_e32 v58, v2
	v_mov_b32_e32 v59, v2
	v_mov_b32_e32 v60, v2
	v_mov_b32_e32 v61, v2
	v_mov_b32_e32 v6, v2
	v_mov_b32_e32 v7, v2
	v_mov_b32_e32 v8, v2
	v_mov_b32_e32 v9, v2
	v_mov_b32_e32 v14, v2
	v_mov_b32_e32 v15, v2
	v_mov_b32_e32 v16, v2
	v_mov_b32_e32 v17, v2
	v_mov_b32_e32 v22, v2
	v_mov_b32_e32 v23, v2
	v_mov_b32_e32 v24, v2
	v_mov_b32_e32 v25, v2
	v_mov_b32_e32 v30, v2
	v_mov_b32_e32 v31, v2
	v_mov_b32_e32 v32, v2
	v_mov_b32_e32 v33, v2
	v_mov_b32_e32 v38, v2
	v_mov_b32_e32 v39, v2
	v_mov_b32_e32 v40, v2
	v_mov_b32_e32 v41, v2
	v_mov_b32_e32 v46, v2
	v_mov_b32_e32 v47, v2
	v_mov_b32_e32 v48, v2
	v_mov_b32_e32 v49, v2
	v_mov_b32_e32 v54, v2
	v_mov_b32_e32 v55, v2
	v_mov_b32_e32 v56, v2
	v_mov_b32_e32 v57, v2
	v_mov_b32_e32 v62, v2
	v_mov_b32_e32 v63, v2
	v_mov_b32_e32 v64, v2
	v_mov_b32_e32 v65, v2
	v_mov_b32_e32 v66, v2
	v_mov_b32_e32 v67, v2
	v_mov_b32_e32 v68, v2
	v_mov_b32_e32 v69, v2
	v_mov_b32_e32 v74, v2
	v_mov_b32_e32 v75, v2
	v_mov_b32_e32 v76, v2
	v_mov_b32_e32 v77, v2
	v_mov_b32_e32 v82, v2
	v_mov_b32_e32 v83, v2
	v_mov_b32_e32 v84, v2
	v_mov_b32_e32 v85, v2
	v_mov_b32_e32 v90, v2
	v_mov_b32_e32 v91, v2
	v_mov_b32_e32 v92, v2
	v_mov_b32_e32 v93, v2
	v_mov_b32_e32 v98, v2
	v_mov_b32_e32 v99, v2
	v_mov_b32_e32 v100, v2
	v_mov_b32_e32 v101, v2
	v_mov_b32_e32 v106, v2
	v_mov_b32_e32 v107, v2
	v_mov_b32_e32 v108, v2
	v_mov_b32_e32 v109, v2
	v_mov_b32_e32 v114, v2
	v_mov_b32_e32 v115, v2
	v_mov_b32_e32 v116, v2
	v_mov_b32_e32 v117, v2
	v_mov_b32_e32 v122, v2
	v_mov_b32_e32 v123, v2
	v_mov_b32_e32 v124, v2
	v_mov_b32_e32 v125, v2
	v_mov_b32_e32 v70, v2
	v_mov_b32_e32 v71, v2
	v_mov_b32_e32 v72, v2
	v_mov_b32_e32 v73, v2
	v_mov_b32_e32 v78, v2
	v_mov_b32_e32 v79, v2
	v_mov_b32_e32 v80, v2
	v_mov_b32_e32 v81, v2
	v_mov_b32_e32 v86, v2
	v_mov_b32_e32 v87, v2
	v_mov_b32_e32 v88, v2
	v_mov_b32_e32 v89, v2
	v_mov_b32_e32 v94, v2
	v_mov_b32_e32 v95, v2
	v_mov_b32_e32 v96, v2
	v_mov_b32_e32 v97, v2
	v_mov_b32_e32 v102, v2
	v_mov_b32_e32 v103, v2
	v_mov_b32_e32 v104, v2
	v_mov_b32_e32 v105, v2
	v_mov_b32_e32 v110, v2
	v_mov_b32_e32 v111, v2
	v_mov_b32_e32 v112, v2
	v_mov_b32_e32 v113, v2
	v_mov_b32_e32 v118, v2
	v_mov_b32_e32 v119, v2
	v_mov_b32_e32 v120, v2
	v_mov_b32_e32 v121, v2
	v_mov_b32_e32 v126, v2
	v_mov_b32_e32 v127, v2
	v_mov_b32_e32 v128, v2
	v_mov_b32_e32 v129, v2
	v_add_u32_e32 v212, 0x10000, v160
	.p2align 6

.LBB0_1274:
	s_lshl_b64 s[40:41], s[16:17], 15
	s_lshl_b64 s[42:43], s[16:17], 7
	s_and_b64 s[16:17], s[38:39], exec
	s_cselect_b32 s10, s40, 0
	s_cselect_b32 s5, s41, 0
	s_add_u32 s16, s28, s10
	s_addc_u32 s17, s29, s5
	s_and_b64 s[28:29], s[38:39], exec
	s_cselect_b32 s10, s42, 0
	s_cselect_b32 s5, s43, 0
	s_add_u32 s28, s30, s10
	s_addc_u32 s29, s31, s5
	s_cmp_lt_i32 s54, 1
	s_cbranch_scc1 .LBB0_1277
	s_add_i32 s5, s54, -2
	s_add_u32 s44, s6, 0x100
	s_addc_u32 s45, s7, 0
	s_add_u32 s30, s8, 0xc000
	s_addc_u32 s31, s9, 0
	s_mov_b32 s38, 0
	v_add_u32_e32 v172, 0x10000, v210
	.p2align 6
